# adds next-iteration prefetch in the final RMSNorm loop (stores no longer block the loads) and the compute-dtype header comment
# baseline (speedup 1.0000x reference)
.LBB0_942:
	s_cmp_ge_i32 s31, s68
	s_cselect_b64 s[0:1], -1, 0
	s_cmp_lt_i32 s31, s69
	s_cselect_b64 s[8:9], -1, 0
	s_and_b64 s[0:1], s[0:1], s[8:9]
	v_readlane_b32 s20, v251, 31
	v_readlane_b32 s10, v253, 11
	s_and_b64 vcc, exec, s[0:1]
	v_readlane_b32 s21, v251, 32
	v_readlane_b32 s11, v253, 12
	s_cbranch_vccz .LBB0_946
	s_lshl_b32 s0, s2, 12
	s_and_b32 s2, s0, 0x7000
	v_readlane_b32 s0, v253, 10
	s_add_i32 s0, s2, s0
	v_readlane_b32 s1, v251, 24
	s_add_i32 s3, s0, s1
	s_and_b64 s[0:1], s[10:11], exec
	v_readlane_b32 s0, v251, 25
	v_readlane_b32 s1, v251, 26
	s_cselect_b32 s0, s3, s0
	s_add_i32 s1, s2, 0x1000
	s_and_b64 s[2:3], s[10:11], exec
	s_cselect_b32 s3, s1, 0x8000
	s_cmp_ge_i32 s0, s3
	s_cbranch_scc1 .LBB0_946
	v_readlane_b32 s12, v251, 0
	v_readlane_b32 s13, v251, 1
	v_readlane_b32 s14, v251, 2
	v_readlane_b32 s15, v251, 3
	v_readlane_b32 s16, v251, 4
	v_readlane_b32 s17, v251, 5
	v_lshlrev_b32_e32 v20, 5, v223
	v_readlane_b32 s18, v251, 6
	v_readlane_b32 s19, v251, 7
	s_mov_b64 s[12:13], s[16:17]
	s_waitcnt lgkmcnt(0)
	global_load_dwordx4 v[0:3], v20, s[12:13] offset:16
	global_load_dwordx4 v[4:7], v20, s[12:13]
	global_load_dwordx4 v[8:11], v20, s[12:13] offset:2064
	global_load_dwordx4 v[12:15], v20, s[12:13] offset:2048
	v_cmp_lt_i32_e32 vcc, v206, v205
	v_mov_b32_e32 v21, 0
	v_and_b32_e32 v16, 3, v222
	v_cndmask_b32_e32 v17, v204, v206, vcc
	v_lshlrev_b32_e32 v23, 2, v17
	v_xor_b32_e32 v17, 2, v204
	v_cmp_lt_i32_e32 vcc, v17, v205
	s_and_b64 s[10:11], s[10:11], exec
	v_lshlrev_b32_e32 v16, 4, v16
	v_cndmask_b32_e32 v17, v204, v17, vcc
	v_lshlrev_b32_e32 v24, 2, v17
	v_mov_b32_e32 v17, v21
	v_lshl_add_u64 v[16:17], s[20:21], 0, v[16:17]
	s_mov_b64 s[10:11], 0x200000
	v_mov_b32_e32 v155, v21
	s_mov_b64 s[14:15], s[18:19]
	v_readlane_b32 s1, v251, 57
	v_lshl_add_u64 v[16:17], v[16:17], 0, s[10:11]
	v_lshl_add_u64 v[18:19], s[20:21], 0, v[154:155]
	s_mov_b64 s[10:11], 0x6400000
	s_cselect_b32 s12, 0x100, s1
	v_lshl_add_u64 v[18:19], v[18:19], 0, s[10:11]
	v_lshl_add_u64 v[20:21], s[14:15], 0, v[20:21]
	s_mov_b32 s2, 0x3a800000
	v_mov_b32_e32 v22, 0x358637bd
	s_mov_b32 s13, 0x800000
	s_mov_b32 s1, s0
	v_mov_b32_e32 v124, s1
	v_ashrrev_i32_e32 v125, 31, v124
	v_lshlrev_b64 v[126:127], 6, v[124:125]
	v_lshl_add_u64 v[126:127], v[16:17], 0, v[126:127]
	global_load_dwordx4 v[100:103], v[126:127], off
	v_lshlrev_b64 v[128:129], 11, v[124:125]
	v_lshl_add_u64 v[128:129], v[18:19], 0, v[128:129]
	global_load_dwordx4 v[104:107], v[128:129], off
	global_load_dwordx4 v[108:111], v[128:129], off offset:1024
	s_add_i32 s1, s1, s12
	v_mov_b32_e32 v124, s1
	v_ashrrev_i32_e32 v125, 31, v124
	v_lshlrev_b64 v[126:127], 6, v[124:125]
	v_lshl_add_u64 v[126:127], v[16:17], 0, v[126:127]
	global_load_dwordx4 v[112:115], v[126:127], off
	v_lshlrev_b64 v[128:129], 11, v[124:125]
	v_lshl_add_u64 v[128:129], v[18:19], 0, v[128:129]
	global_load_dwordx4 v[116:119], v[128:129], off
	global_load_dwordx4 v[120:123], v[128:129], off offset:1024
	s_waitcnt vmcnt(0)
.LBB0_945:
	s_ashr_i32 s1, s0, 31
	s_lshl_b64 s[10:11], s[0:1], 6
	v_lshl_add_u64 v[26:27], v[16:17], 0, s[10:11]
	s_lshl_b64 s[10:11], s[0:1], 11
	v_lshl_add_u64 v[34:35], v[18:19], 0, s[10:11]
	s_add_i32 s10, s0, s12
	s_ashr_i32 s11, s10, 31
	s_lshl_b64 s[14:15], s[10:11], 6
	v_lshl_add_u64 v[38:39], v[16:17], 0, s[14:15]
	s_nop 0
	s_lshl_b64 s[14:15], s[10:11], 11
	v_lshl_add_u64 v[46:47], v[18:19], 0, s[14:15]
	s_nop 0
	s_lshl_b64 s[0:1], s[0:1], 12
	v_lshl_add_u64 v[54:55], v[20:21], 0, s[0:1]
	s_lshl_b64 s[0:1], s[10:11], 12
	v_lshl_add_u64 v[56:57], v[20:21], 0, s[0:1]
	s_waitcnt vmcnt(8)
	v_mov_b32_e32 v26, v100
	v_mov_b32_e32 v27, v101
	v_mov_b32_e32 v28, v102
	v_mov_b32_e32 v29, v103
	v_mov_b32_e32 v30, v104
	v_mov_b32_e32 v31, v105
	v_mov_b32_e32 v32, v106
	v_mov_b32_e32 v33, v107
	v_mov_b32_e32 v34, v108
	v_mov_b32_e32 v35, v109
	v_mov_b32_e32 v36, v110
	v_mov_b32_e32 v37, v111
	v_mov_b32_e32 v38, v112
	v_mov_b32_e32 v39, v113
	v_mov_b32_e32 v40, v114
	v_mov_b32_e32 v41, v115
	v_mov_b32_e32 v42, v116
	v_mov_b32_e32 v43, v117
	v_mov_b32_e32 v44, v118
	v_mov_b32_e32 v45, v119
	v_mov_b32_e32 v46, v120
	v_mov_b32_e32 v47, v121
	v_mov_b32_e32 v48, v122
	v_mov_b32_e32 v49, v123
	s_add_i32 s1, s10, s12
	v_mov_b32_e32 v124, s1
	v_ashrrev_i32_e32 v125, 31, v124
	v_lshlrev_b64 v[126:127], 6, v[124:125]
	v_lshl_add_u64 v[126:127], v[16:17], 0, v[126:127]
	global_load_dwordx4 v[100:103], v[126:127], off
	v_lshlrev_b64 v[128:129], 11, v[124:125]
	v_lshl_add_u64 v[128:129], v[18:19], 0, v[128:129]
	global_load_dwordx4 v[104:107], v[128:129], off
	global_load_dwordx4 v[108:111], v[128:129], off offset:1024
	s_add_i32 s1, s1, s12
	v_mov_b32_e32 v124, s1
	v_ashrrev_i32_e32 v125, 31, v124
	v_lshlrev_b64 v[126:127], 6, v[124:125]
	v_lshl_add_u64 v[126:127], v[16:17], 0, v[126:127]
	global_load_dwordx4 v[112:115], v[126:127], off
	v_lshlrev_b64 v[128:129], 11, v[124:125]
	v_lshl_add_u64 v[128:129], v[18:19], 0, v[128:129]
	global_load_dwordx4 v[116:119], v[128:129], off
	global_load_dwordx4 v[120:123], v[128:129], off offset:1024
	v_mov_b32_e32 v50, v27
	v_mov_b32_e32 v51, v28
	v_mov_b32_e32 v27, v29
	v_pk_add_f32 v[26:27], v[50:51], v[26:27]
	v_mov_b32_e32 v50, v39
	v_mov_b32_e32 v51, v40
	v_mov_b32_e32 v39, v41
	v_pk_add_f32 v[38:39], v[50:51], v[38:39]
	v_mov_b32_e32 v51, v26
	v_mov_b32_e32 v50, v38
	v_mov_b32_e32 v26, v39
	v_pk_add_f32 v[26:27], v[50:51], v[26:27]
	ds_bpermute_b32 v39, v23, v27
	ds_bpermute_b32 v38, v23, v26
	v_lshlrev_b32_e32 v28, 16, v30
	v_and_b32_e32 v29, 0xffff0000, v30
	v_lshlrev_b32_e32 v30, 16, v31
	v_and_b32_e32 v31, 0xffff0000, v31
	s_waitcnt lgkmcnt(0)
	v_pk_add_f32 v[26:27], v[26:27], v[38:39]
	ds_bpermute_b32 v39, v24, v27
	ds_bpermute_b32 v38, v24, v26
	v_lshlrev_b32_e32 v52, 16, v32
	v_and_b32_e32 v53, 0xffff0000, v32
	v_lshlrev_b32_e32 v32, 16, v33
	v_and_b32_e32 v33, 0xffff0000, v33
	s_waitcnt lgkmcnt(0)
	v_pk_add_f32 v[26:27], v[26:27], v[38:39]
	v_lshlrev_b32_e32 v58, 16, v34
	v_pk_fma_f32 v[26:27], v[26:27], s[2:3], v[22:23] op_sel_hi:[1,0,0]
	v_and_b32_e32 v59, 0xffff0000, v34
	v_mul_f32_e32 v25, 0x4b800000, v27
	v_cmp_gt_f32_e32 vcc, s13, v27
	v_mul_f32_e32 v38, 0x4b800000, v26
	v_cmp_gt_f32_e64 s[0:1], s13, v26
	v_cndmask_b32_e32 v25, v27, v25, vcc
	v_rsq_f32_e32 v25, v25
	v_cndmask_b32_e64 v26, v26, v38, s[0:1]
	v_rsq_f32_e32 v27, v26
	v_lshlrev_b32_e32 v34, 16, v35
	v_mul_f32_e32 v26, 0x45800000, v25
	v_cndmask_b32_e32 v26, v25, v26, vcc
	v_mul_f32_e32 v38, 0x45800000, v27
	v_and_b32_e32 v35, 0xffff0000, v35
	v_lshlrev_b32_e32 v60, 16, v36
	v_and_b32_e32 v61, 0xffff0000, v36
	v_lshlrev_b32_e32 v36, 16, v37
	v_and_b32_e32 v37, 0xffff0000, v37
	v_lshlrev_b32_e32 v40, 16, v42
	v_and_b32_e32 v41, 0xffff0000, v42
	v_lshlrev_b32_e32 v42, 16, v43
	v_and_b32_e32 v43, 0xffff0000, v43
	v_lshlrev_b32_e32 v50, 16, v44
	v_and_b32_e32 v51, 0xffff0000, v44
	v_lshlrev_b32_e32 v44, 16, v45
	v_and_b32_e32 v45, 0xffff0000, v45
	v_lshlrev_b32_e32 v64, 16, v48
	v_and_b32_e32 v65, 0xffff0000, v48
	v_cndmask_b32_e64 v48, v27, v38, s[0:1]
	v_pk_mul_f32 v[38:39], v[26:27], v[28:29] op_sel_hi:[0,1]
	v_pk_mul_f32 v[28:29], v[26:27], v[30:31] op_sel_hi:[0,1]
	v_lshlrev_b32_e32 v62, 16, v46
	v_and_b32_e32 v63, 0xffff0000, v46
	v_lshlrev_b32_e32 v46, 16, v47
	v_and_b32_e32 v47, 0xffff0000, v47
	v_pk_mul_f32 v[30:31], v[26:27], v[52:53] op_sel_hi:[0,1]
	v_pk_mul_f32 v[32:33], v[26:27], v[32:33] op_sel_hi:[0,1]
	v_pk_mul_f32 v[52:53], v[26:27], v[58:59] op_sel_hi:[0,1]
	v_pk_mul_f32 v[34:35], v[26:27], v[34:35] op_sel_hi:[0,1]
	v_pk_mul_f32 v[58:59], v[26:27], v[60:61] op_sel_hi:[0,1]
	v_pk_mul_f32 v[60:61], v[26:27], v[36:37] op_sel_hi:[0,1]
	v_pk_mul_f32 v[66:67], v[48:49], v[40:41] op_sel_hi:[0,1]
	v_pk_mul_f32 v[42:43], v[48:49], v[42:43] op_sel_hi:[0,1]
	v_pk_mul_f32 v[50:51], v[48:49], v[50:51] op_sel_hi:[0,1]
	v_pk_mul_f32 v[68:69], v[48:49], v[44:45] op_sel_hi:[0,1]
	v_pk_mul_f32 v[28:29], v[6:7], v[28:29]
	v_pk_mul_f32 v[26:27], v[4:5], v[38:39]
	v_pk_mul_f32 v[32:33], v[2:3], v[32:33]
	v_pk_mul_f32 v[30:31], v[0:1], v[30:31]
	v_pk_mul_f32 v[36:37], v[14:15], v[34:35]
	v_pk_mul_f32 v[34:35], v[12:13], v[52:53]
	v_pk_mul_f32 v[40:41], v[10:11], v[60:61]
	v_pk_mul_f32 v[38:39], v[8:9], v[58:59]
	v_pk_mul_f32 v[44:45], v[6:7], v[42:43]
	v_pk_mul_f32 v[42:43], v[4:5], v[66:67]
	v_pk_mul_f32 v[52:53], v[2:3], v[68:69]
	v_pk_mul_f32 v[50:51], v[0:1], v[50:51]
	global_store_dwordx4 v[54:55], v[26:29], off
	global_store_dwordx4 v[54:55], v[30:33], off offset:16
	global_store_dwordx4 v[54:55], v[34:37], off offset:2048
	global_store_dwordx4 v[54:55], v[38:41], off offset:2064
	global_store_dwordx4 v[56:57], v[42:45], off
	global_store_dwordx4 v[56:57], v[50:53], off offset:16
	v_pk_mul_f32 v[26:27], v[48:49], v[62:63] op_sel_hi:[0,1]
	v_pk_mul_f32 v[28:29], v[48:49], v[46:47] op_sel_hi:[0,1]
	v_lshlrev_b32_e32 v30, 16, v49
	v_and_b32_e32 v31, 0xffff0000, v49
	v_pk_mul_f32 v[28:29], v[14:15], v[28:29]
	v_pk_mul_f32 v[26:27], v[12:13], v[26:27]
	global_store_dwordx4 v[56:57], v[26:29], off offset:2048
	s_add_i32 s0, s10, s12
	s_cmp_lt_i32 s0, s3
	v_pk_mul_f32 v[26:27], v[48:49], v[64:65] op_sel_hi:[0,1]
	v_pk_mul_f32 v[28:29], v[48:49], v[30:31] op_sel_hi:[0,1]
	v_pk_mul_f32 v[28:29], v[10:11], v[28:29]
	v_pk_mul_f32 v[26:27], v[8:9], v[26:27]
	global_store_dwordx4 v[56:57], v[26:29], off offset:2064
	s_cbranch_scc1 .LBB0_945
